# softmax: scale-fma, row-sum adds and bf16 packs placed between the v_exp ops (3 per exp)
# speedup vs baseline: 1.0048x; 1.0048x over previous
.LBB0_517:
	v_cndmask_b32_e64 v231, v234, v231, s[4:5]
	v_mul_f32_e32 v237, 0xbe0293ee, v231
	v_fmamk_f32 v128, v128, 0x3e0293ee, v237
	v_fmamk_f32 v129, v129, 0x3e0293ee, v237
	v_fmamk_f32 v130, v130, 0x3e0293ee, v237
	v_fmamk_f32 v131, v131, 0x3e0293ee, v237
	v_exp_f32_e32 v192, v128
	v_fmamk_f32 v132, v132, 0x3e0293ee, v237
	v_exp_f32_e32 v193, v129
	v_fmamk_f32 v133, v133, 0x3e0293ee, v237
	v_exp_f32_e32 v194, v130
	v_fmamk_f32 v134, v134, 0x3e0293ee, v237
	v_exp_f32_e32 v195, v131
	v_fmamk_f32 v135, v135, 0x3e0293ee, v237
	v_exp_f32_e32 v196, v132
	v_fmamk_f32 v136, v136, 0x3e0293ee, v237
	v_exp_f32_e32 v197, v133
	v_fmamk_f32 v137, v137, 0x3e0293ee, v237
	v_exp_f32_e32 v198, v134
	v_fmamk_f32 v138, v138, 0x3e0293ee, v237
	v_add_f32_e32 v236, v192, v193
	v_exp_f32_e32 v199, v135
	v_fmamk_f32 v139, v139, 0x3e0293ee, v237
	v_add_f32_e32 v236, v194, v236
	v_exp_f32_e32 v200, v136
	v_fmamk_f32 v140, v140, 0x3e0293ee, v237
	v_add_f32_e32 v236, v195, v236
	v_exp_f32_e32 v201, v137
	v_fmamk_f32 v141, v141, 0x3e0293ee, v237
	v_add_f32_e32 v236, v196, v236
	v_exp_f32_e32 v202, v138
	v_fmamk_f32 v142, v142, 0x3e0293ee, v237
	v_add_f32_e32 v236, v197, v236
	v_exp_f32_e32 v203, v139
	v_fmamk_f32 v143, v143, 0x3e0293ee, v237
	v_add_f32_e32 v236, v198, v236
	v_exp_f32_e32 v204, v140
	v_fmamk_f32 v144, v144, 0x3e0293ee, v237
	v_add_f32_e32 v236, v199, v236
	v_exp_f32_e32 v205, v141
	v_fmamk_f32 v145, v145, 0x3e0293ee, v237
	v_add_f32_e32 v236, v200, v236
	v_exp_f32_e32 v206, v142
	v_fmamk_f32 v146, v146, 0x3e0293ee, v237
	v_add_f32_e32 v236, v201, v236
	v_exp_f32_e32 v207, v143
	v_fmamk_f32 v147, v147, 0x3e0293ee, v237
	v_add_f32_e32 v236, v202, v236
	v_cvt_pk_bf16_f32 v132, v192, v193
	v_exp_f32_e32 v144, v144
	v_fmamk_f32 v148, v148, 0x3e0293ee, v237
	v_add_f32_e32 v236, v203, v236
	v_cvt_pk_bf16_f32 v133, v194, v195
	v_exp_f32_e32 v145, v145
	v_fmamk_f32 v149, v149, 0x3e0293ee, v237
	v_add_f32_e32 v236, v204, v236
	v_cvt_pk_bf16_f32 v134, v196, v197
	v_exp_f32_e32 v146, v146
	v_fmamk_f32 v150, v150, 0x3e0293ee, v237
	v_add_f32_e32 v236, v205, v236
	v_cvt_pk_bf16_f32 v135, v198, v199
	v_exp_f32_e32 v147, v147
	v_fmamk_f32 v151, v151, 0x3e0293ee, v237
	v_add_f32_e32 v236, v206, v236
	v_cvt_pk_bf16_f32 v140, v200, v201
	v_exp_f32_e32 v148, v148
	v_fmamk_f32 v152, v152, 0x3e0293ee, v237
	v_add_f32_e32 v236, v207, v236
	v_cvt_pk_bf16_f32 v141, v202, v203
	v_exp_f32_e32 v149, v149
	v_fmamk_f32 v153, v153, 0x3e0293ee, v237
	v_add_f32_e32 v236, v144, v236
	v_cvt_pk_bf16_f32 v142, v204, v205
	v_exp_f32_e32 v150, v150
	v_fmamk_f32 v154, v154, 0x3e0293ee, v237
	v_add_f32_e32 v236, v145, v236
	v_cvt_pk_bf16_f32 v143, v206, v207
	v_exp_f32_e32 v151, v151
	v_fmamk_f32 v155, v155, 0x3e0293ee, v237
	v_add_f32_e32 v236, v146, v236
	v_cvt_pk_bf16_f32 v128, v144, v145
	v_exp_f32_e32 v152, v152
	v_fmamk_f32 v156, v156, 0x3e0293ee, v237
	v_add_f32_e32 v236, v147, v236
	v_cvt_pk_bf16_f32 v129, v146, v147
	v_exp_f32_e32 v153, v153
	v_fmamk_f32 v157, v157, 0x3e0293ee, v237
	v_add_f32_e32 v236, v148, v236
	v_cvt_pk_bf16_f32 v130, v148, v149
	v_exp_f32_e32 v154, v154
	v_fmamk_f32 v158, v158, 0x3e0293ee, v237
	v_add_f32_e32 v236, v149, v236
	v_cvt_pk_bf16_f32 v131, v150, v151
	v_exp_f32_e32 v155, v155
	v_fmamk_f32 v159, v159, 0x3e0293ee, v237
	v_add_f32_e32 v236, v150, v236
	v_exp_f32_e32 v156, v156
	v_add_f32_e32 v236, v151, v236
	v_cvt_pk_bf16_f32 v136, v152, v153
	v_exp_f32_e32 v157, v157
	v_add_f32_e32 v236, v152, v236
	v_exp_f32_e32 v158, v158
	v_add_f32_e32 v236, v153, v236
	v_cvt_pk_bf16_f32 v137, v154, v155
	v_exp_f32_e32 v159, v159
	v_add_f32_e32 v236, v154, v236
	v_add_f32_e32 v236, v155, v236
	v_add_f32_e32 v236, v156, v236
	v_add_f32_e32 v236, v157, v236
	v_cvt_pk_bf16_f32 v138, v156, v157
	v_add_f32_e32 v236, v158, v236
	v_add_f32_e32 v236, v159, v236
	v_cvt_pk_bf16_f32 v139, v158, v159
	v_mov_b32_e32 v237, v236
	s_nop 1
	v_permlane32_swap_b32_e32 v236, v237
	v_add_f32_e32 v144, v236, v237
	v_fmac_f32_e32 v144, v232, v233
	v_lshl_add_u32 v145, s76, 15, v230
	ds_read_b64_tr_b16 v[146:147], v145 offset:0
	ds_read_b64_tr_b16 v[148:149], v145 offset:4096
	ds_read_b64_tr_b16 v[150:151], v145 offset:8192
	ds_read_b64_tr_b16 v[152:153], v145 offset:12288
	ds_read_b64_tr_b16 v[154:155], v145 offset:16384
	ds_read_b64_tr_b16 v[156:157], v145 offset:20480
	ds_read_b64_tr_b16 v[192:193], v145 offset:24576
	ds_read_b64_tr_b16 v[194:195], v145 offset:28672
	ds_read_b64_tr_b16 v[196:197], v145 offset:512
	ds_read_b64_tr_b16 v[198:199], v145 offset:4608
	ds_read_b64_tr_b16 v[200:201], v145 offset:8704
	ds_read_b64_tr_b16 v[202:203], v145 offset:12800
	ds_read_b64_tr_b16 v[204:205], v145 offset:16896
	ds_read_b64_tr_b16 v[206:207], v145 offset:20992
	s_waitcnt lgkmcnt(12)
	s_nop 0
	v_mfma_f32_32x32x16_bf16 v[0:15], v[128:131], v[146:149], v[0:15]
	ds_read_b64_tr_b16 v[232:233], v145 offset:25088
	ds_read_b64_tr_b16 v[234:235], v145 offset:29184
	s_waitcnt lgkmcnt(12)
	v_mfma_f32_32x32x16_bf16 v[0:15], v[136:139], v[150:153], v[0:15]
	ds_read_b64_tr_b16 v[146:147], v145 offset:1024
	ds_read_b64_tr_b16 v[148:149], v145 offset:5120
	s_waitcnt lgkmcnt(12)
	v_mfma_f32_32x32x16_bf16 v[0:15], v[132:135], v[154:157], v[0:15]
	ds_read_b64_tr_b16 v[150:151], v145 offset:9216
	ds_read_b64_tr_b16 v[152:153], v145 offset:13312
	s_waitcnt lgkmcnt(12)
	v_mfma_f32_32x32x16_bf16 v[0:15], v[140:143], v[192:195], v[0:15]
	ds_read_b64_tr_b16 v[154:155], v145 offset:17408
	ds_read_b64_tr_b16 v[156:157], v145 offset:21504
	s_waitcnt lgkmcnt(12)
	v_mfma_f32_32x32x16_bf16 v[112:127], v[128:131], v[196:199], v[112:127]
	ds_read_b64_tr_b16 v[192:193], v145 offset:25600
	ds_read_b64_tr_b16 v[194:195], v145 offset:29696
	s_waitcnt lgkmcnt(12)
	v_mfma_f32_32x32x16_bf16 v[112:127], v[136:139], v[200:203], v[112:127]
	ds_read_b64_tr_b16 v[196:197], v145 offset:1536
	ds_read_b64_tr_b16 v[198:199], v145 offset:5632
	s_waitcnt lgkmcnt(12)
	v_mfma_f32_32x32x16_bf16 v[112:127], v[132:135], v[204:207], v[112:127]
	ds_read_b64_tr_b16 v[200:201], v145 offset:9728
	ds_read_b64_tr_b16 v[202:203], v145 offset:13824
	s_waitcnt lgkmcnt(12)
	v_mfma_f32_32x32x16_bf16 v[112:127], v[140:143], v[232:235], v[112:127]
	ds_read_b64_tr_b16 v[204:205], v145 offset:17920
	ds_read_b64_tr_b16 v[206:207], v145 offset:22016
	s_waitcnt lgkmcnt(12)
	v_mfma_f32_32x32x16_bf16 v[96:111], v[128:131], v[146:149], v[96:111]
	ds_read_b64_tr_b16 v[232:233], v145 offset:26112
	ds_read_b64_tr_b16 v[234:235], v145 offset:30208
	s_waitcnt lgkmcnt(12)
	v_mfma_f32_32x32x16_bf16 v[96:111], v[136:139], v[150:153], v[96:111]
	ds_read_b64_tr_b16 v[146:147], v145 offset:2048
	ds_read_b64_tr_b16 v[148:149], v145 offset:6144
	s_waitcnt lgkmcnt(12)
	v_mfma_f32_32x32x16_bf16 v[96:111], v[132:135], v[154:157], v[96:111]
	ds_read_b64_tr_b16 v[150:151], v145 offset:10240
	ds_read_b64_tr_b16 v[152:153], v145 offset:14336
	s_waitcnt lgkmcnt(12)
	v_mfma_f32_32x32x16_bf16 v[96:111], v[140:143], v[192:195], v[96:111]
	ds_read_b64_tr_b16 v[154:155], v145 offset:18432
	ds_read_b64_tr_b16 v[156:157], v145 offset:22528
	s_waitcnt lgkmcnt(12)
	v_mfma_f32_32x32x16_bf16 v[80:95], v[128:131], v[196:199], v[80:95]
	ds_read_b64_tr_b16 v[192:193], v145 offset:26624
	ds_read_b64_tr_b16 v[194:195], v145 offset:30720
	s_waitcnt lgkmcnt(12)
	v_mfma_f32_32x32x16_bf16 v[80:95], v[136:139], v[200:203], v[80:95]
	ds_read_b64_tr_b16 v[196:197], v145 offset:2560
	ds_read_b64_tr_b16 v[198:199], v145 offset:6656
	s_waitcnt lgkmcnt(12)
	v_mfma_f32_32x32x16_bf16 v[80:95], v[132:135], v[204:207], v[80:95]
	ds_read_b64_tr_b16 v[200:201], v145 offset:10752
	ds_read_b64_tr_b16 v[202:203], v145 offset:14848
	s_waitcnt lgkmcnt(12)
	v_mfma_f32_32x32x16_bf16 v[80:95], v[140:143], v[232:235], v[80:95]
	ds_read_b64_tr_b16 v[204:205], v145 offset:18944
	ds_read_b64_tr_b16 v[206:207], v145 offset:23040
	s_waitcnt lgkmcnt(12)
	v_mfma_f32_32x32x16_bf16 v[64:79], v[128:131], v[146:149], v[64:79]
	ds_read_b64_tr_b16 v[232:233], v145 offset:27136
	ds_read_b64_tr_b16 v[234:235], v145 offset:31232
	s_waitcnt lgkmcnt(12)
	v_mfma_f32_32x32x16_bf16 v[64:79], v[136:139], v[150:153], v[64:79]
	ds_read_b64_tr_b16 v[146:147], v145 offset:3072
	ds_read_b64_tr_b16 v[148:149], v145 offset:7168
	s_waitcnt lgkmcnt(12)
	v_mfma_f32_32x32x16_bf16 v[64:79], v[132:135], v[154:157], v[64:79]
	ds_read_b64_tr_b16 v[150:151], v145 offset:11264
	ds_read_b64_tr_b16 v[152:153], v145 offset:15360
	s_waitcnt lgkmcnt(12)
	v_mfma_f32_32x32x16_bf16 v[64:79], v[140:143], v[192:195], v[64:79]
	ds_read_b64_tr_b16 v[154:155], v145 offset:19456
	ds_read_b64_tr_b16 v[156:157], v145 offset:23552
	s_waitcnt lgkmcnt(12)
	v_mfma_f32_32x32x16_bf16 v[48:63], v[128:131], v[196:199], v[48:63]
	ds_read_b64_tr_b16 v[192:193], v145 offset:27648
	ds_read_b64_tr_b16 v[194:195], v145 offset:31744
	s_waitcnt lgkmcnt(12)
	v_mfma_f32_32x32x16_bf16 v[48:63], v[136:139], v[200:203], v[48:63]
	ds_read_b64_tr_b16 v[196:197], v145 offset:3584
	ds_read_b64_tr_b16 v[198:199], v145 offset:7680
	s_waitcnt lgkmcnt(12)
	v_mfma_f32_32x32x16_bf16 v[48:63], v[132:135], v[204:207], v[48:63]
	ds_read_b64_tr_b16 v[200:201], v145 offset:11776
	ds_read_b64_tr_b16 v[202:203], v145 offset:15872
	s_waitcnt lgkmcnt(12)
	v_mfma_f32_32x32x16_bf16 v[48:63], v[140:143], v[232:235], v[48:63]
	ds_read_b64_tr_b16 v[204:205], v145 offset:19968
	ds_read_b64_tr_b16 v[206:207], v145 offset:24064
	s_waitcnt lgkmcnt(12)
	v_mfma_f32_32x32x16_bf16 v[32:47], v[128:131], v[146:149], v[32:47]
	ds_read_b64_tr_b16 v[232:233], v145 offset:28160
	ds_read_b64_tr_b16 v[234:235], v145 offset:32256
	s_waitcnt lgkmcnt(12)
	v_mfma_f32_32x32x16_bf16 v[32:47], v[136:139], v[150:153], v[32:47]
	s_waitcnt lgkmcnt(10)
	v_mfma_f32_32x32x16_bf16 v[32:47], v[132:135], v[154:157], v[32:47]
	s_waitcnt lgkmcnt(8)
	v_mfma_f32_32x32x16_bf16 v[32:47], v[140:143], v[192:195], v[32:47]
	s_waitcnt lgkmcnt(6)
	v_mfma_f32_32x32x16_bf16 v[16:31], v[128:131], v[196:199], v[16:31]
	s_add_i32 s4, s76, 1
	s_cmp_lg_u32 s76, 2
	s_cselect_b32 s76, s4, 0
	s_add_i32 s4, s74, 1
	s_cmp_lg_u32 s74, 2
	s_cselect_b32 s74, s4, 0
	s_add_u32 s22, s22, 0x20000
	s_waitcnt lgkmcnt(4)
	v_mfma_f32_32x32x16_bf16 v[16:31], v[136:139], v[200:203], v[16:31]
	s_addc_u32 s23, s23, 0
	s_add_i32 s86, s86, 1
	s_cmp_eq_u32 s22, 0x800000
	s_waitcnt lgkmcnt(2)
	v_mfma_f32_32x32x16_bf16 v[16:31], v[132:135], v[204:207], v[16:31]
	s_waitcnt lgkmcnt(0)
	v_mfma_f32_32x32x16_bf16 v[16:31], v[140:143], v[232:235], v[16:31]
	s_cbranch_scc1 .LBB0_521
	v_mov_b32_e32 v232, v144
	s_cmp_eq_u32 s22, 0x7e0000
	s_mov_b64 s[4:5], -1
	s_cbranch_scc1 .LBB0_510

.LBB0_910:
	v_cndmask_b32_e64 v231, v234, v231, s[4:5]
	v_mul_f32_e32 v237, 0xbe0293ee, v231
	v_fmamk_f32 v128, v128, 0x3e0293ee, v237
	v_fmamk_f32 v129, v129, 0x3e0293ee, v237
	v_fmamk_f32 v130, v130, 0x3e0293ee, v237
	v_fmamk_f32 v131, v131, 0x3e0293ee, v237
	v_exp_f32_e32 v192, v128
	v_fmamk_f32 v132, v132, 0x3e0293ee, v237
	v_exp_f32_e32 v193, v129
	v_fmamk_f32 v133, v133, 0x3e0293ee, v237
	v_exp_f32_e32 v194, v130
	v_fmamk_f32 v134, v134, 0x3e0293ee, v237
	v_exp_f32_e32 v195, v131
	v_fmamk_f32 v135, v135, 0x3e0293ee, v237
	v_exp_f32_e32 v196, v132
	v_fmamk_f32 v136, v136, 0x3e0293ee, v237
	v_exp_f32_e32 v197, v133
	v_fmamk_f32 v137, v137, 0x3e0293ee, v237
	v_exp_f32_e32 v198, v134
	v_fmamk_f32 v138, v138, 0x3e0293ee, v237
	v_add_f32_e32 v236, v192, v193
	v_exp_f32_e32 v199, v135
	v_fmamk_f32 v139, v139, 0x3e0293ee, v237
	v_add_f32_e32 v236, v194, v236
	v_exp_f32_e32 v200, v136
	v_fmamk_f32 v140, v140, 0x3e0293ee, v237
	v_add_f32_e32 v236, v195, v236
	v_exp_f32_e32 v201, v137
	v_fmamk_f32 v141, v141, 0x3e0293ee, v237
	v_add_f32_e32 v236, v196, v236
	v_exp_f32_e32 v202, v138
	v_fmamk_f32 v142, v142, 0x3e0293ee, v237
	v_add_f32_e32 v236, v197, v236
	v_exp_f32_e32 v203, v139
	v_fmamk_f32 v143, v143, 0x3e0293ee, v237
	v_add_f32_e32 v236, v198, v236
	v_exp_f32_e32 v204, v140
	v_fmamk_f32 v144, v144, 0x3e0293ee, v237
	v_add_f32_e32 v236, v199, v236
	v_exp_f32_e32 v205, v141
	v_fmamk_f32 v145, v145, 0x3e0293ee, v237
	v_add_f32_e32 v236, v200, v236
	v_exp_f32_e32 v206, v142
	v_fmamk_f32 v146, v146, 0x3e0293ee, v237
	v_add_f32_e32 v236, v201, v236
	v_exp_f32_e32 v207, v143
	v_fmamk_f32 v147, v147, 0x3e0293ee, v237
	v_add_f32_e32 v236, v202, v236
	v_cvt_pk_bf16_f32 v132, v192, v193
	v_exp_f32_e32 v144, v144
	v_fmamk_f32 v148, v148, 0x3e0293ee, v237
	v_add_f32_e32 v236, v203, v236
	v_cvt_pk_bf16_f32 v133, v194, v195
	v_exp_f32_e32 v145, v145
	v_fmamk_f32 v149, v149, 0x3e0293ee, v237
	v_add_f32_e32 v236, v204, v236
	v_cvt_pk_bf16_f32 v134, v196, v197
	v_exp_f32_e32 v146, v146
	v_fmamk_f32 v150, v150, 0x3e0293ee, v237
	v_add_f32_e32 v236, v205, v236
	v_cvt_pk_bf16_f32 v135, v198, v199
	v_exp_f32_e32 v147, v147
	v_fmamk_f32 v151, v151, 0x3e0293ee, v237
	v_add_f32_e32 v236, v206, v236
	v_cvt_pk_bf16_f32 v140, v200, v201
	v_exp_f32_e32 v148, v148
	v_fmamk_f32 v152, v152, 0x3e0293ee, v237
	v_add_f32_e32 v236, v207, v236
	v_cvt_pk_bf16_f32 v141, v202, v203
	v_exp_f32_e32 v149, v149
	v_fmamk_f32 v153, v153, 0x3e0293ee, v237
	v_add_f32_e32 v236, v144, v236
	v_cvt_pk_bf16_f32 v142, v204, v205
	v_exp_f32_e32 v150, v150
	v_fmamk_f32 v154, v154, 0x3e0293ee, v237
	v_add_f32_e32 v236, v145, v236
	v_cvt_pk_bf16_f32 v143, v206, v207
	v_exp_f32_e32 v151, v151
	v_fmamk_f32 v155, v155, 0x3e0293ee, v237
	v_add_f32_e32 v236, v146, v236
	v_cvt_pk_bf16_f32 v128, v144, v145
	v_exp_f32_e32 v152, v152
	v_fmamk_f32 v156, v156, 0x3e0293ee, v237
	v_add_f32_e32 v236, v147, v236
	v_cvt_pk_bf16_f32 v129, v146, v147
	v_exp_f32_e32 v153, v153
	v_fmamk_f32 v157, v157, 0x3e0293ee, v237
	v_add_f32_e32 v236, v148, v236
	v_cvt_pk_bf16_f32 v130, v148, v149
	v_exp_f32_e32 v154, v154
	v_fmamk_f32 v158, v158, 0x3e0293ee, v237
	v_add_f32_e32 v236, v149, v236
	v_cvt_pk_bf16_f32 v131, v150, v151
	v_exp_f32_e32 v155, v155
	v_fmamk_f32 v159, v159, 0x3e0293ee, v237
	v_add_f32_e32 v236, v150, v236
	v_exp_f32_e32 v156, v156
	v_add_f32_e32 v236, v151, v236
	v_cvt_pk_bf16_f32 v136, v152, v153
	v_exp_f32_e32 v157, v157
	v_add_f32_e32 v236, v152, v236
	v_exp_f32_e32 v158, v158
	v_add_f32_e32 v236, v153, v236
	v_cvt_pk_bf16_f32 v137, v154, v155
	v_exp_f32_e32 v159, v159
	v_add_f32_e32 v236, v154, v236
	v_add_f32_e32 v236, v155, v236
	v_add_f32_e32 v236, v156, v236
	v_add_f32_e32 v236, v157, v236
	v_cvt_pk_bf16_f32 v138, v156, v157
	v_add_f32_e32 v236, v158, v236
	v_add_f32_e32 v236, v159, v236
	v_cvt_pk_bf16_f32 v139, v158, v159
	v_mov_b32_e32 v237, v236
	s_nop 1
	v_permlane32_swap_b32_e32 v236, v237
	v_add_f32_e32 v144, v236, v237
	v_fmac_f32_e32 v144, v232, v233
	v_lshl_add_u32 v145, s80, 15, v230
	ds_read_b64_tr_b16 v[146:147], v145 offset:0
	ds_read_b64_tr_b16 v[148:149], v145 offset:4096
	ds_read_b64_tr_b16 v[150:151], v145 offset:8192
	ds_read_b64_tr_b16 v[152:153], v145 offset:12288
	ds_read_b64_tr_b16 v[154:155], v145 offset:16384
	ds_read_b64_tr_b16 v[156:157], v145 offset:20480
	ds_read_b64_tr_b16 v[192:193], v145 offset:24576
	ds_read_b64_tr_b16 v[194:195], v145 offset:28672
	ds_read_b64_tr_b16 v[196:197], v145 offset:512
	ds_read_b64_tr_b16 v[198:199], v145 offset:4608
	ds_read_b64_tr_b16 v[200:201], v145 offset:8704
	ds_read_b64_tr_b16 v[202:203], v145 offset:12800
	ds_read_b64_tr_b16 v[204:205], v145 offset:16896
	ds_read_b64_tr_b16 v[206:207], v145 offset:20992
	s_waitcnt lgkmcnt(12)
	s_nop 0
	v_mfma_f32_32x32x16_bf16 v[0:15], v[128:131], v[146:149], v[0:15]
	ds_read_b64_tr_b16 v[232:233], v145 offset:25088
	ds_read_b64_tr_b16 v[234:235], v145 offset:29184
	s_waitcnt lgkmcnt(12)
	v_mfma_f32_32x32x16_bf16 v[0:15], v[136:139], v[150:153], v[0:15]
	ds_read_b64_tr_b16 v[146:147], v145 offset:1024
	ds_read_b64_tr_b16 v[148:149], v145 offset:5120
	s_waitcnt lgkmcnt(12)
	v_mfma_f32_32x32x16_bf16 v[0:15], v[132:135], v[154:157], v[0:15]
	ds_read_b64_tr_b16 v[150:151], v145 offset:9216
	ds_read_b64_tr_b16 v[152:153], v145 offset:13312
	s_waitcnt lgkmcnt(12)
	v_mfma_f32_32x32x16_bf16 v[0:15], v[140:143], v[192:195], v[0:15]
	ds_read_b64_tr_b16 v[154:155], v145 offset:17408
	ds_read_b64_tr_b16 v[156:157], v145 offset:21504
	s_waitcnt lgkmcnt(12)
	v_mfma_f32_32x32x16_bf16 v[112:127], v[128:131], v[196:199], v[112:127]
	ds_read_b64_tr_b16 v[192:193], v145 offset:25600
	ds_read_b64_tr_b16 v[194:195], v145 offset:29696
	s_waitcnt lgkmcnt(12)
	v_mfma_f32_32x32x16_bf16 v[112:127], v[136:139], v[200:203], v[112:127]
	ds_read_b64_tr_b16 v[196:197], v145 offset:1536
	ds_read_b64_tr_b16 v[198:199], v145 offset:5632
	s_waitcnt lgkmcnt(12)
	v_mfma_f32_32x32x16_bf16 v[112:127], v[132:135], v[204:207], v[112:127]
	ds_read_b64_tr_b16 v[200:201], v145 offset:9728
	ds_read_b64_tr_b16 v[202:203], v145 offset:13824
	s_waitcnt lgkmcnt(12)
	v_mfma_f32_32x32x16_bf16 v[112:127], v[140:143], v[232:235], v[112:127]
	ds_read_b64_tr_b16 v[204:205], v145 offset:17920
	ds_read_b64_tr_b16 v[206:207], v145 offset:22016
	s_waitcnt lgkmcnt(12)
	v_mfma_f32_32x32x16_bf16 v[96:111], v[128:131], v[146:149], v[96:111]
	ds_read_b64_tr_b16 v[232:233], v145 offset:26112
	ds_read_b64_tr_b16 v[234:235], v145 offset:30208
	s_waitcnt lgkmcnt(12)
	v_mfma_f32_32x32x16_bf16 v[96:111], v[136:139], v[150:153], v[96:111]
	ds_read_b64_tr_b16 v[146:147], v145 offset:2048
	ds_read_b64_tr_b16 v[148:149], v145 offset:6144
	s_waitcnt lgkmcnt(12)
	v_mfma_f32_32x32x16_bf16 v[96:111], v[132:135], v[154:157], v[96:111]
	ds_read_b64_tr_b16 v[150:151], v145 offset:10240
	ds_read_b64_tr_b16 v[152:153], v145 offset:14336
	s_waitcnt lgkmcnt(12)
	v_mfma_f32_32x32x16_bf16 v[96:111], v[140:143], v[192:195], v[96:111]
	ds_read_b64_tr_b16 v[154:155], v145 offset:18432
	ds_read_b64_tr_b16 v[156:157], v145 offset:22528
	s_waitcnt lgkmcnt(12)
	v_mfma_f32_32x32x16_bf16 v[80:95], v[128:131], v[196:199], v[80:95]
	ds_read_b64_tr_b16 v[192:193], v145 offset:26624
	ds_read_b64_tr_b16 v[194:195], v145 offset:30720
	s_waitcnt lgkmcnt(12)
	v_mfma_f32_32x32x16_bf16 v[80:95], v[136:139], v[200:203], v[80:95]
	ds_read_b64_tr_b16 v[196:197], v145 offset:2560
	ds_read_b64_tr_b16 v[198:199], v145 offset:6656
	s_waitcnt lgkmcnt(12)
	v_mfma_f32_32x32x16_bf16 v[80:95], v[132:135], v[204:207], v[80:95]
	ds_read_b64_tr_b16 v[200:201], v145 offset:10752
	ds_read_b64_tr_b16 v[202:203], v145 offset:14848
	s_waitcnt lgkmcnt(12)
	v_mfma_f32_32x32x16_bf16 v[80:95], v[140:143], v[232:235], v[80:95]
	ds_read_b64_tr_b16 v[204:205], v145 offset:18944
	ds_read_b64_tr_b16 v[206:207], v145 offset:23040
	s_waitcnt lgkmcnt(12)
	v_mfma_f32_32x32x16_bf16 v[64:79], v[128:131], v[146:149], v[64:79]
	ds_read_b64_tr_b16 v[232:233], v145 offset:27136
	ds_read_b64_tr_b16 v[234:235], v145 offset:31232
	s_waitcnt lgkmcnt(12)
	v_mfma_f32_32x32x16_bf16 v[64:79], v[136:139], v[150:153], v[64:79]
	ds_read_b64_tr_b16 v[146:147], v145 offset:3072
	ds_read_b64_tr_b16 v[148:149], v145 offset:7168
	s_waitcnt lgkmcnt(12)
	v_mfma_f32_32x32x16_bf16 v[64:79], v[132:135], v[154:157], v[64:79]
	ds_read_b64_tr_b16 v[150:151], v145 offset:11264
	ds_read_b64_tr_b16 v[152:153], v145 offset:15360
	s_waitcnt lgkmcnt(12)
	v_mfma_f32_32x32x16_bf16 v[64:79], v[140:143], v[192:195], v[64:79]
	ds_read_b64_tr_b16 v[154:155], v145 offset:19456
	ds_read_b64_tr_b16 v[156:157], v145 offset:23552
	s_waitcnt lgkmcnt(12)
	v_mfma_f32_32x32x16_bf16 v[48:63], v[128:131], v[196:199], v[48:63]
	ds_read_b64_tr_b16 v[192:193], v145 offset:27648
	ds_read_b64_tr_b16 v[194:195], v145 offset:31744
	s_waitcnt lgkmcnt(12)
	v_mfma_f32_32x32x16_bf16 v[48:63], v[136:139], v[200:203], v[48:63]
	ds_read_b64_tr_b16 v[196:197], v145 offset:3584
	ds_read_b64_tr_b16 v[198:199], v145 offset:7680
	s_waitcnt lgkmcnt(12)
	v_mfma_f32_32x32x16_bf16 v[48:63], v[132:135], v[204:207], v[48:63]
	ds_read_b64_tr_b16 v[200:201], v145 offset:11776
	ds_read_b64_tr_b16 v[202:203], v145 offset:15872
	s_waitcnt lgkmcnt(12)
	v_mfma_f32_32x32x16_bf16 v[48:63], v[140:143], v[232:235], v[48:63]
	ds_read_b64_tr_b16 v[204:205], v145 offset:19968
	ds_read_b64_tr_b16 v[206:207], v145 offset:24064
	s_waitcnt lgkmcnt(12)
	v_mfma_f32_32x32x16_bf16 v[32:47], v[128:131], v[146:149], v[32:47]
	ds_read_b64_tr_b16 v[232:233], v145 offset:28160
	ds_read_b64_tr_b16 v[234:235], v145 offset:32256
	s_waitcnt lgkmcnt(12)
	v_mfma_f32_32x32x16_bf16 v[32:47], v[136:139], v[150:153], v[32:47]
	s_waitcnt lgkmcnt(10)
	v_mfma_f32_32x32x16_bf16 v[32:47], v[132:135], v[154:157], v[32:47]
	s_waitcnt lgkmcnt(8)
	v_mfma_f32_32x32x16_bf16 v[32:47], v[140:143], v[192:195], v[32:47]
	s_waitcnt lgkmcnt(6)
	v_mfma_f32_32x32x16_bf16 v[16:31], v[128:131], v[196:199], v[16:31]
	s_add_i32 s4, s80, 1
	s_cmp_lg_u32 s80, 2
	s_cselect_b32 s80, s4, 0
	s_add_i32 s4, s78, 1
	s_cmp_lg_u32 s78, 2
	s_cselect_b32 s78, s4, 0
	s_add_u32 s22, s22, 0x20000
	s_waitcnt lgkmcnt(4)
	v_mfma_f32_32x32x16_bf16 v[16:31], v[136:139], v[200:203], v[16:31]
	s_addc_u32 s23, s23, 0
	s_add_i32 s86, s86, 1
	s_cmp_eq_u32 s22, 0x800000
	s_waitcnt lgkmcnt(2)
	v_mfma_f32_32x32x16_bf16 v[16:31], v[132:135], v[204:207], v[16:31]
	s_waitcnt lgkmcnt(0)
	v_mfma_f32_32x32x16_bf16 v[16:31], v[140:143], v[232:235], v[16:31]
	s_cbranch_scc1 .LBB0_914
	v_mov_b32_e32 v232, v144
	s_cmp_eq_u32 s22, 0x7e0000
	s_mov_b64 s[4:5], -1
	s_cbranch_scc1 .LBB0_903
